# gate/up K-loop load segments: LDS-DMA group issued after the fragment reads returned (lgkmcnt(0) first); other loops unchanged; on top of no-setprio + group barriers
# baseline (speedup 1.0000x reference)
.LBB0_350:
	s_add_u32 s46, s30, 0x1fc000
	s_addc_u32 s47, s31, 0
	s_and_b64 s[36:37], exec, s[36:37]
	s_cselect_b32 s46, s78, s46
	s_cselect_b32 s47, s19, s47
	s_add_u32 s36, s46, 0x200000
	s_addc_u32 s37, s47, 0
	s_add_i32 s79, 0, 0x10000
	s_add_i32 s86, 0, 0x14000
	ds_read_b128 v[148:151], v145
	ds_read_b128 v[152:155], v145 offset:1024
	ds_read_b128 v[156:159], v145 offset:2048
	ds_read_b128 v[160:163], v145 offset:3072
	ds_read_b128 v[164:167], v145 offset:16384
	ds_read_b128 v[168:171], v145 offset:17408
	ds_read_b128 v[172:175], v145 offset:18432
	ds_read_b128 v[176:179], v145 offset:19456
	ds_read_b128 v[180:183], v146
	ds_read_b128 v[184:187], v146 offset:1024
	ds_read_b128 v[188:191], v146 offset:2048
	ds_read_b128 v[192:195], v146 offset:3072
	ds_read_b128 v[200:203], v146 offset:4096
	ds_read_b128 v[204:207], v146 offset:5120
	ds_read_b128 v[208:211], v146 offset:6144
	ds_read_b128 v[222:225], v146 offset:7168
	s_waitcnt lgkmcnt(0)
	s_add_i32 m0, s61, 0xc000
	s_nop 0
	global_load_lds_dwordx4 v140, s[30:31]
	s_add_i32 m0, s61, 0xe000
	s_nop 0
	global_load_lds_dwordx4 v142, s[30:31]
	s_waitcnt vmcnt(8)
	s_barrier
	v_mfma_f32_16x16x32_bf16 v[128:131], v[148:151], v[180:183], v[128:131]
	v_mfma_f32_16x16x32_bf16 v[124:127], v[156:159], v[180:183], v[124:127]
	v_mfma_f32_16x16x32_bf16 v[112:115], v[148:151], v[188:191], v[112:115]
	v_mfma_f32_16x16x32_bf16 v[108:111], v[156:159], v[188:191], v[108:111]
	v_mfma_f32_16x16x32_bf16 v[96:99], v[148:151], v[200:203], v[96:99]
	v_mfma_f32_16x16x32_bf16 v[92:95], v[156:159], v[200:203], v[92:95]
	v_mfma_f32_16x16x32_bf16 v[80:83], v[148:151], v[208:211], v[80:83]
	v_mfma_f32_16x16x32_bf16 v[76:79], v[156:159], v[208:211], v[76:79]
	v_mfma_f32_16x16x32_bf16 v[128:131], v[152:155], v[184:187], v[128:131]
	v_mfma_f32_16x16x32_bf16 v[124:127], v[160:163], v[184:187], v[124:127]
	v_mfma_f32_16x16x32_bf16 v[112:115], v[152:155], v[192:195], v[112:115]
	v_mfma_f32_16x16x32_bf16 v[108:111], v[160:163], v[192:195], v[108:111]
	v_mfma_f32_16x16x32_bf16 v[96:99], v[152:155], v[204:207], v[96:99]
	v_mfma_f32_16x16x32_bf16 v[92:95], v[160:163], v[204:207], v[92:95]
	v_mfma_f32_16x16x32_bf16 v[80:83], v[152:155], v[222:225], v[80:83]
	v_mfma_f32_16x16x32_bf16 v[76:79], v[160:163], v[222:225], v[76:79]
	v_mfma_f32_16x16x32_bf16 v[120:123], v[164:167], v[180:183], v[120:123]
	v_mfma_f32_16x16x32_bf16 v[116:119], v[172:175], v[180:183], v[116:119]
	v_mfma_f32_16x16x32_bf16 v[104:107], v[164:167], v[188:191], v[104:107]
	v_mfma_f32_16x16x32_bf16 v[100:103], v[172:175], v[188:191], v[100:103]
	v_mfma_f32_16x16x32_bf16 v[88:91], v[164:167], v[200:203], v[88:91]
	v_mfma_f32_16x16x32_bf16 v[84:87], v[172:175], v[200:203], v[84:87]
	v_mfma_f32_16x16x32_bf16 v[72:75], v[164:167], v[208:211], v[72:75]
	v_mfma_f32_16x16x32_bf16 v[68:71], v[172:175], v[208:211], v[68:71]
	v_mfma_f32_16x16x32_bf16 v[120:123], v[168:171], v[184:187], v[120:123]
	v_mfma_f32_16x16x32_bf16 v[116:119], v[176:179], v[184:187], v[116:119]
	v_mfma_f32_16x16x32_bf16 v[104:107], v[168:171], v[192:195], v[104:107]
	v_mfma_f32_16x16x32_bf16 v[100:103], v[176:179], v[192:195], v[100:103]
	v_mfma_f32_16x16x32_bf16 v[88:91], v[168:171], v[204:207], v[88:91]
	v_mfma_f32_16x16x32_bf16 v[84:87], v[176:179], v[204:207], v[84:87]
	v_mfma_f32_16x16x32_bf16 v[72:75], v[168:171], v[222:225], v[72:75]
	v_mfma_f32_16x16x32_bf16 v[68:71], v[176:179], v[222:225], v[68:71]
	s_barrier
	s_add_i32 s79, s79, s58
	ds_read_b128 v[180:183], v146 offset:16384
	ds_read_b128 v[184:187], v146 offset:17408
	ds_read_b128 v[188:191], v146 offset:18432
	ds_read_b128 v[192:195], v146 offset:19456
	ds_read_b128 v[200:203], v146 offset:20480
	ds_read_b128 v[204:207], v146 offset:21504
	ds_read_b128 v[208:211], v146 offset:22528
	ds_read_b128 v[222:225], v146 offset:23552
	s_waitcnt lgkmcnt(0)
	s_mov_b32 m0, s79
	s_nop 0
	global_load_lds_dwordx4 v136, s[44:45]
	s_add_i32 m0, s79, 0x2000
	s_add_u32 s82, s44, 0x4000
	s_addc_u32 s83, s45, 0
	s_add_i32 s79, s86, s58
	global_load_lds_dwordx4 v132, s[44:45]
	s_mov_b32 m0, s79
	s_nop 0
	global_load_lds_dwordx4 v136, s[82:83]
	s_add_i32 m0, s79, 0x2000
	s_nop 0
	global_load_lds_dwordx4 v132, s[82:83]
	s_mov_b32 m0, s61
	s_nop 0
	global_load_lds_dwordx4 v138, s[46:47]
	s_mov_b32 m0, s66
	s_nop 0
	global_load_lds_dwordx4 v134, s[46:47]
	s_waitcnt vmcnt(8)
	s_barrier
	v_mfma_f32_16x16x32_bf16 v[64:67], v[148:151], v[180:183], v[64:67]
	v_mfma_f32_16x16x32_bf16 v[60:63], v[156:159], v[180:183], v[60:63]
	v_mfma_f32_16x16x32_bf16 v[48:51], v[148:151], v[188:191], v[48:51]
	v_mfma_f32_16x16x32_bf16 v[44:47], v[156:159], v[188:191], v[44:47]
	v_mfma_f32_16x16x32_bf16 v[32:35], v[148:151], v[200:203], v[32:35]
	v_mfma_f32_16x16x32_bf16 v[28:31], v[156:159], v[200:203], v[28:31]
	v_mfma_f32_16x16x32_bf16 v[12:15], v[148:151], v[208:211], v[12:15]
	v_mfma_f32_16x16x32_bf16 v[16:19], v[156:159], v[208:211], v[16:19]
	v_mfma_f32_16x16x32_bf16 v[64:67], v[152:155], v[184:187], v[64:67]
	v_mfma_f32_16x16x32_bf16 v[60:63], v[160:163], v[184:187], v[60:63]
	v_mfma_f32_16x16x32_bf16 v[48:51], v[152:155], v[192:195], v[48:51]
	v_mfma_f32_16x16x32_bf16 v[44:47], v[160:163], v[192:195], v[44:47]
	v_mfma_f32_16x16x32_bf16 v[32:35], v[152:155], v[204:207], v[32:35]
	v_mfma_f32_16x16x32_bf16 v[28:31], v[160:163], v[204:207], v[28:31]
	v_mfma_f32_16x16x32_bf16 v[12:15], v[152:155], v[222:225], v[12:15]
	v_mfma_f32_16x16x32_bf16 v[16:19], v[160:163], v[222:225], v[16:19]
	v_mfma_f32_16x16x32_bf16 v[56:59], v[164:167], v[180:183], v[56:59]
	v_mfma_f32_16x16x32_bf16 v[52:55], v[172:175], v[180:183], v[52:55]
	v_mfma_f32_16x16x32_bf16 v[40:43], v[164:167], v[188:191], v[40:43]
	v_mfma_f32_16x16x32_bf16 v[36:39], v[172:175], v[188:191], v[36:39]
	v_mfma_f32_16x16x32_bf16 v[24:27], v[164:167], v[200:203], v[24:27]
	v_mfma_f32_16x16x32_bf16 v[20:23], v[172:175], v[200:203], v[20:23]
	v_mfma_f32_16x16x32_bf16 v[4:7], v[164:167], v[208:211], v[4:7]
	v_mfma_f32_16x16x32_bf16 v[8:11], v[172:175], v[208:211], v[8:11]
	v_mfma_f32_16x16x32_bf16 v[56:59], v[168:171], v[184:187], v[56:59]
	v_mfma_f32_16x16x32_bf16 v[52:55], v[176:179], v[184:187], v[52:55]
	v_mfma_f32_16x16x32_bf16 v[40:43], v[168:171], v[192:195], v[40:43]
	v_mfma_f32_16x16x32_bf16 v[36:39], v[176:179], v[192:195], v[36:39]
	v_mfma_f32_16x16x32_bf16 v[24:27], v[168:171], v[204:207], v[24:27]
	v_mfma_f32_16x16x32_bf16 v[20:23], v[176:179], v[204:207], v[20:23]
	v_mfma_f32_16x16x32_bf16 v[4:7], v[168:171], v[222:225], v[4:7]
	v_mfma_f32_16x16x32_bf16 v[8:11], v[176:179], v[222:225], v[8:11]
	s_barrier
	s_add_i32 s79, 0, 0x18000
	s_add_i32 s82, 0, 0x1c000
	ds_read_b128 v[148:151], v145 offset:32768
	ds_read_b128 v[152:155], v145 offset:33792
	ds_read_b128 v[156:159], v145 offset:34816
	ds_read_b128 v[160:163], v145 offset:35840
	ds_read_b128 v[164:167], v145 offset:49152
	ds_read_b128 v[168:171], v145 offset:50176
	ds_read_b128 v[172:175], v145 offset:51200
	ds_read_b128 v[176:179], v145 offset:52224
	s_add_u32 s46, s46, 0x4000
	s_addc_u32 s47, s47, 0
	ds_read_b128 v[180:183], v146 offset:32768
	ds_read_b128 v[184:187], v146 offset:33792
	ds_read_b128 v[188:191], v146 offset:34816
	ds_read_b128 v[192:195], v146 offset:35840
	ds_read_b128 v[200:203], v146 offset:36864
	ds_read_b128 v[204:207], v146 offset:37888
	ds_read_b128 v[208:211], v146 offset:38912
	ds_read_b128 v[222:225], v146 offset:39936
	s_waitcnt lgkmcnt(0)
	s_mov_b32 m0, s67
	s_nop 0
	global_load_lds_dwordx4 v138, s[46:47]
	s_mov_b32 m0, s70
	s_nop 0
	global_load_lds_dwordx4 v134, s[46:47]
	s_waitcnt vmcnt(8)
	s_barrier
	v_mfma_f32_16x16x32_bf16 v[128:131], v[148:151], v[180:183], v[128:131]
	v_mfma_f32_16x16x32_bf16 v[124:127], v[156:159], v[180:183], v[124:127]
	v_mfma_f32_16x16x32_bf16 v[112:115], v[148:151], v[188:191], v[112:115]
	v_mfma_f32_16x16x32_bf16 v[108:111], v[156:159], v[188:191], v[108:111]
	v_mfma_f32_16x16x32_bf16 v[96:99], v[148:151], v[200:203], v[96:99]
	v_mfma_f32_16x16x32_bf16 v[92:95], v[156:159], v[200:203], v[92:95]
	v_mfma_f32_16x16x32_bf16 v[80:83], v[148:151], v[208:211], v[80:83]
	v_mfma_f32_16x16x32_bf16 v[76:79], v[156:159], v[208:211], v[76:79]
	v_mfma_f32_16x16x32_bf16 v[128:131], v[152:155], v[184:187], v[128:131]
	v_mfma_f32_16x16x32_bf16 v[124:127], v[160:163], v[184:187], v[124:127]
	v_mfma_f32_16x16x32_bf16 v[112:115], v[152:155], v[192:195], v[112:115]
	v_mfma_f32_16x16x32_bf16 v[108:111], v[160:163], v[192:195], v[108:111]
	v_mfma_f32_16x16x32_bf16 v[96:99], v[152:155], v[204:207], v[96:99]
	v_mfma_f32_16x16x32_bf16 v[92:95], v[160:163], v[204:207], v[92:95]
	v_mfma_f32_16x16x32_bf16 v[80:83], v[152:155], v[222:225], v[80:83]
	v_mfma_f32_16x16x32_bf16 v[76:79], v[160:163], v[222:225], v[76:79]
	v_mfma_f32_16x16x32_bf16 v[120:123], v[164:167], v[180:183], v[120:123]
	v_mfma_f32_16x16x32_bf16 v[116:119], v[172:175], v[180:183], v[116:119]
	v_mfma_f32_16x16x32_bf16 v[104:107], v[164:167], v[188:191], v[104:107]
	v_mfma_f32_16x16x32_bf16 v[100:103], v[172:175], v[188:191], v[100:103]
	v_mfma_f32_16x16x32_bf16 v[88:91], v[164:167], v[200:203], v[88:91]
	v_mfma_f32_16x16x32_bf16 v[84:87], v[172:175], v[200:203], v[84:87]
	v_mfma_f32_16x16x32_bf16 v[72:75], v[164:167], v[208:211], v[72:75]
	v_mfma_f32_16x16x32_bf16 v[68:71], v[172:175], v[208:211], v[68:71]
	v_mfma_f32_16x16x32_bf16 v[120:123], v[168:171], v[184:187], v[120:123]
	v_mfma_f32_16x16x32_bf16 v[116:119], v[176:179], v[184:187], v[116:119]
	v_mfma_f32_16x16x32_bf16 v[104:107], v[168:171], v[192:195], v[104:107]
	v_mfma_f32_16x16x32_bf16 v[100:103], v[176:179], v[192:195], v[100:103]
	v_mfma_f32_16x16x32_bf16 v[88:91], v[168:171], v[204:207], v[88:91]
	v_mfma_f32_16x16x32_bf16 v[84:87], v[176:179], v[204:207], v[84:87]
	v_mfma_f32_16x16x32_bf16 v[72:75], v[168:171], v[222:225], v[72:75]
	v_mfma_f32_16x16x32_bf16 v[68:71], v[176:179], v[222:225], v[68:71]
	s_barrier
	s_add_u32 s46, s44, 0x160000
	s_addc_u32 s47, s45, 0
	s_add_i32 s79, s79, s58
	ds_read_b128 v[180:183], v146 offset:49152
	ds_read_b128 v[184:187], v146 offset:50176
	ds_read_b128 v[188:191], v146 offset:51200
	ds_read_b128 v[192:195], v146 offset:52224
	ds_read_b128 v[200:203], v146 offset:53248
	ds_read_b128 v[204:207], v146 offset:54272
	ds_read_b128 v[208:211], v146 offset:55296
	ds_read_b128 v[222:225], v146 offset:56320
	s_waitcnt lgkmcnt(0)
	s_mov_b32 m0, s79
	s_nop 0
	global_load_lds_dwordx4 v136, s[46:47]
	s_add_i32 m0, s79, 0x2000
	s_add_u32 s44, s44, 0x164000
	s_addc_u32 s45, s45, 0
	global_load_lds_dwordx4 v132, s[46:47]
	s_add_i32 s46, s82, s58
	s_mov_b32 m0, s46
	s_nop 0
	global_load_lds_dwordx4 v136, s[44:45]
	s_add_i32 m0, s46, 0x2000
	s_nop 0
	global_load_lds_dwordx4 v132, s[44:45]
	s_mov_b32 m0, s75
	s_nop 0
	global_load_lds_dwordx4 v138, s[36:37]
	s_mov_b32 m0, s76
	s_nop 0
	global_load_lds_dwordx4 v134, s[36:37]
	s_waitcnt vmcnt(8)
	s_barrier
	v_mfma_f32_16x16x32_bf16 v[64:67], v[148:151], v[180:183], v[64:67]
	v_mfma_f32_16x16x32_bf16 v[60:63], v[156:159], v[180:183], v[60:63]
	v_mfma_f32_16x16x32_bf16 v[48:51], v[148:151], v[188:191], v[48:51]
	v_mfma_f32_16x16x32_bf16 v[44:47], v[156:159], v[188:191], v[44:47]
	v_mfma_f32_16x16x32_bf16 v[32:35], v[148:151], v[200:203], v[32:35]
	v_mfma_f32_16x16x32_bf16 v[28:31], v[156:159], v[200:203], v[28:31]
	v_mfma_f32_16x16x32_bf16 v[12:15], v[148:151], v[208:211], v[12:15]
	v_mfma_f32_16x16x32_bf16 v[16:19], v[156:159], v[208:211], v[16:19]
	v_mfma_f32_16x16x32_bf16 v[64:67], v[152:155], v[184:187], v[64:67]
	v_mfma_f32_16x16x32_bf16 v[60:63], v[160:163], v[184:187], v[60:63]
	v_mfma_f32_16x16x32_bf16 v[48:51], v[152:155], v[192:195], v[48:51]
	v_mfma_f32_16x16x32_bf16 v[44:47], v[160:163], v[192:195], v[44:47]
	v_mfma_f32_16x16x32_bf16 v[32:35], v[152:155], v[204:207], v[32:35]
	v_mfma_f32_16x16x32_bf16 v[28:31], v[160:163], v[204:207], v[28:31]
	v_mfma_f32_16x16x32_bf16 v[12:15], v[152:155], v[222:225], v[12:15]
	v_mfma_f32_16x16x32_bf16 v[16:19], v[160:163], v[222:225], v[16:19]
	v_mfma_f32_16x16x32_bf16 v[56:59], v[164:167], v[180:183], v[56:59]
	v_mfma_f32_16x16x32_bf16 v[52:55], v[172:175], v[180:183], v[52:55]
	v_mfma_f32_16x16x32_bf16 v[40:43], v[164:167], v[188:191], v[40:43]
	v_mfma_f32_16x16x32_bf16 v[36:39], v[172:175], v[188:191], v[36:39]
	v_mfma_f32_16x16x32_bf16 v[24:27], v[164:167], v[200:203], v[24:27]
	v_mfma_f32_16x16x32_bf16 v[20:23], v[172:175], v[200:203], v[20:23]
	v_mfma_f32_16x16x32_bf16 v[4:7], v[164:167], v[208:211], v[4:7]
	v_mfma_f32_16x16x32_bf16 v[8:11], v[172:175], v[208:211], v[8:11]
	v_mfma_f32_16x16x32_bf16 v[56:59], v[168:171], v[184:187], v[56:59]
	v_mfma_f32_16x16x32_bf16 v[52:55], v[176:179], v[184:187], v[52:55]
	v_mfma_f32_16x16x32_bf16 v[40:43], v[168:171], v[192:195], v[40:43]
	v_mfma_f32_16x16x32_bf16 v[36:39], v[176:179], v[192:195], v[36:39]
	v_mfma_f32_16x16x32_bf16 v[24:27], v[168:171], v[204:207], v[24:27]
	v_mfma_f32_16x16x32_bf16 v[20:23], v[176:179], v[204:207], v[20:23]
	v_mfma_f32_16x16x32_bf16 v[4:7], v[168:171], v[222:225], v[4:7]
	v_mfma_f32_16x16x32_bf16 v[8:11], v[176:179], v[222:225], v[8:11]
	s_barrier
	s_add_i32 s15, s15, 2
	s_add_u32 s28, s28, 0x2c0000
	s_addc_u32 s29, s29, 0
	s_add_u32 s30, s30, 0x400000
	s_addc_u32 s31, s31, 0
	s_cmp_gt_u32 s15, 29
	s_cbranch_scc1 .LBB0_353
